# attention K/V LDS-DMA loads marked non-temporal
# speedup vs baseline: 1.0144x; 1.0018x over previous
.Latt_roles_1:
	s_add_i32 s4, s65, 1
	v_cvt_f32_ubyte0_e32 v0, s4
	v_mul_f32_e32 v0, -0.5, v0
	v_exp_f32_e32 v0, v0
	s_nop 1
	v_mul_f32_e32 v20, 0x3fb8aa3b, v0
	s_mov_b32 s4, 0
	s_lshr_b32 s11, s4, 4
	s_and_b32 s12, s4, 15
	s_lshl_b32 s28, s11, 1
	s_lshl_b32 s13, s64, 4
	s_add_i32 s13, s13, s12
	s_lshr_b32 s14, s12, 2
	s_and_b32 s15, s12, 3
	s_lshl_b32 s16, s64, 2
	s_add_i32 s15, s16, s15
	s_cmp_eq_u32 s11, 1
	s_cselect_b32 s29, s14, 0
	s_cselect_b32 s30, s15, s13
	s_cmp_eq_u32 s11, 2
	s_cselect_b32 s29, s12, s29
	s_cselect_b32 s30, s64, s30
	s_mov_b32 s88, 0
	s_mov_b32 s89, 0
	s_lshl_b32 s5, s88, 7
	s_lshl_b32 s6, s67, 3
	s_add_i32 s5, s5, s6
	s_add_i32 s6, s30, -1
	s_lshl_b32 s6, s6, 7
	s_cmp_eq_u32 s89, 1
	s_cbranch_scc1 .Latt_half_2
	s_add_i32 s7, s5, 0
	s_and_b32 s7, s7, 511
	s_lshl_b32 s7, s7, 7
	s_add_i32 m0, s7, s4
	s_add_i32 s7, s6, 0
	v_add_u32_e32 v0, s7, v14
	v_lshlrev_b32_e32 v0, s28, v0
	v_add_u32_e32 v0, s29, v0
	v_max_i32_e32 v0, 0, v0
	v_lshl_or_b32 v2, v0, 7, v15
	v_lshl_add_u64 v[38:39], s[36:37], 0, v[2:3]
	global_load_lds_dwordx4 v[38:39], off nt
	s_add_i32 s7, s5, 64
	s_and_b32 s7, s7, 511
	s_lshl_b32 s7, s7, 7
	s_add_i32 m0, s7, s4
	s_add_i32 s7, s6, 64
	v_add_u32_e32 v0, s7, v14
	v_lshlrev_b32_e32 v0, s28, v0
	v_add_u32_e32 v0, s29, v0
	v_max_i32_e32 v0, 0, v0
	v_lshl_or_b32 v2, v0, 7, v15
	v_lshl_add_u64 v[40:41], s[36:37], 0, v[2:3]
	global_load_lds_dwordx4 v[40:41], off nt
.Latt_half_2:
	s_add_i32 s7, s5, 128
	s_and_b32 s7, s7, 511
	s_lshl_b32 s7, s7, 7
	s_add_i32 m0, s7, s4
	s_add_i32 s7, s6, 128
	v_add_u32_e32 v0, s7, v14
	v_lshlrev_b32_e32 v0, s28, v0
	v_add_u32_e32 v0, s29, v0
	v_max_i32_e32 v0, 0, v0
	v_lshl_or_b32 v2, v0, 7, v15
	v_lshl_add_u64 v[42:43], s[36:37], 0, v[2:3]
	global_load_lds_dwordx4 v[42:43], off nt
	s_add_i32 s7, s5, 192
	s_and_b32 s7, s7, 511
	s_lshl_b32 s7, s7, 7
	s_add_i32 m0, s7, s4
	s_add_i32 s7, s6, 192
	v_add_u32_e32 v0, s7, v14
	v_lshlrev_b32_e32 v0, s28, v0
	v_add_u32_e32 v0, s29, v0
	v_max_i32_e32 v0, 0, v0
	v_lshl_or_b32 v2, v0, 7, v15
	v_lshl_add_u64 v[44:45], s[36:37], 0, v[2:3]
	global_load_lds_dwordx4 v[44:45], off nt
	s_mov_b32 s9, 0x10000
	s_lshl_b32 s5, s88, 7
	s_lshl_b32 s6, s67, 3
	s_add_i32 s5, s5, s6
	s_add_i32 s6, s30, -1
	s_lshl_b32 s6, s6, 7
	s_cmp_eq_u32 s89, 1
	s_cbranch_scc1 .Latt_half_3
	s_add_i32 s7, s5, 0
	s_and_b32 s7, s7, 511
	s_lshl_b32 s7, s7, 7
	s_add_i32 m0, s7, s9
	s_add_i32 s7, s6, 0
	v_add_u32_e32 v0, s7, v14
	v_lshlrev_b32_e32 v0, s28, v0
	v_add_u32_e32 v0, s29, v0
	v_max_i32_e32 v0, 0, v0
	v_lshl_or_b32 v2, v0, 7, v15
	v_lshl_add_u64 v[38:39], s[38:39], 0, v[2:3]
	global_load_lds_dwordx4 v[38:39], off nt
	s_add_i32 s7, s5, 64
	s_and_b32 s7, s7, 511
	s_lshl_b32 s7, s7, 7
	s_add_i32 m0, s7, s9
	s_add_i32 s7, s6, 64
	v_add_u32_e32 v0, s7, v14
	v_lshlrev_b32_e32 v0, s28, v0
	v_add_u32_e32 v0, s29, v0
	v_max_i32_e32 v0, 0, v0
	v_lshl_or_b32 v2, v0, 7, v15
	v_lshl_add_u64 v[40:41], s[38:39], 0, v[2:3]
	global_load_lds_dwordx4 v[40:41], off nt
.Latt_half_3:
	s_add_i32 s7, s5, 128
	s_and_b32 s7, s7, 511
	s_lshl_b32 s7, s7, 7
	s_add_i32 m0, s7, s9
	s_add_i32 s7, s6, 128
	v_add_u32_e32 v0, s7, v14
	v_lshlrev_b32_e32 v0, s28, v0
	v_add_u32_e32 v0, s29, v0
	v_max_i32_e32 v0, 0, v0
	v_lshl_or_b32 v2, v0, 7, v15
	v_lshl_add_u64 v[42:43], s[38:39], 0, v[2:3]
	global_load_lds_dwordx4 v[42:43], off nt
	s_add_i32 s7, s5, 192
	s_and_b32 s7, s7, 511
	s_lshl_b32 s7, s7, 7
	s_add_i32 m0, s7, s9
	s_add_i32 s7, s6, 192
	v_add_u32_e32 v0, s7, v14
	v_lshlrev_b32_e32 v0, s28, v0
	v_add_u32_e32 v0, s29, v0
	v_max_i32_e32 v0, 0, v0
	v_lshl_or_b32 v2, v0, 7, v15
	v_lshl_add_u64 v[44:45], s[38:39], 0, v[2:3]
	global_load_lds_dwordx4 v[44:45], off nt
	s_lshl_b32 s5, s30, 7
	v_add_u32_e32 v82, s5, v17
	v_lshlrev_b32_e32 v82, s28, v82
	v_add_u32_e32 v82, s29, v82
	v_lshl_add_u32 v1, v82, 11, v18
	global_load_dwordx4 v[48:51], v1, s[40:41]
	global_load_dwordx4 v[52:55], v1, s[40:41] offset:64
	s_cmp_lt_u32 s4, 16
	s_cbranch_scc1 .Latt_odummy_4
	v_lshl_add_u32 v1, v82, 11, v19
	global_load_dwordx2 v[64:65], v1, s[42:43] offset:0
	global_load_dwordx2 v[66:67], v1, s[42:43] offset:32
	global_load_dwordx2 v[68:69], v1, s[42:43] offset:64
	global_load_dwordx2 v[70:71], v1, s[42:43] offset:96
	v_lshlrev_b32_e32 v0, 2, v82
	global_load_dword v80, v0, s[44:45]
	s_branch .Latt_odone_5

.Latt_odone_7:
	s_waitcnt vmcnt(0)
	s_barrier
	s_cmp_eq_u32 s68, 0
	s_cbranch_scc1 .Latt_lead_8
	s_mov_b32 s4, 1
	s_lshr_b32 s11, s4, 4
	s_and_b32 s12, s4, 15
	s_lshl_b32 s28, s11, 1
	s_lshl_b32 s13, s64, 4
	s_add_i32 s13, s13, s12
	s_lshr_b32 s14, s12, 2
	s_and_b32 s15, s12, 3
	s_lshl_b32 s16, s64, 2
	s_add_i32 s15, s16, s15
	s_cmp_eq_u32 s11, 1
	s_cselect_b32 s29, s14, 0
	s_cselect_b32 s30, s15, s13
	s_cmp_eq_u32 s11, 2
	s_cselect_b32 s29, s12, s29
	s_cselect_b32 s30, s64, s30
	s_lshr_b32 s11, s4, 4
	s_and_b32 s12, s4, 15
	s_and_b32 s13, s12, 3
	s_cmp_lg_u32 s12, 0
	s_cselect_b32 s14, 1, 0
	s_lshr_b32 s15, s12, 2
	s_and_b32 s16, s12, 3
	s_add_i32 s15, s15, s16
	s_add_i32 s15, s15, 1
	s_and_b32 s15, s15, 3
	s_cmp_lg_u32 s16, 0
	s_cselect_b32 s16, 1, 0
	s_cmp_eq_u32 s11, 1
	s_cselect_b32 s13, s15, s13
	s_cselect_b32 s14, s16, s14
	s_and_b32 s15, s12, 1
	s_lshl_b32 s15, s15, 1
	s_add_i32 s15, s15, 1
	s_cmp_eq_u32 s11, 2
	s_cselect_b32 s88, s15, s13
	s_cselect_b32 s89, 0, s14
	s_lshl_b32 s5, s88, 7
	s_lshl_b32 s6, s67, 3
	s_add_i32 s5, s5, s6
	s_add_i32 s6, s30, -1
	s_lshl_b32 s6, s6, 7
	s_cmp_eq_u32 s89, 1
	s_cbranch_scc1 .Latt_half_9
	s_add_i32 s7, s5, 0
	s_and_b32 s7, s7, 511
	s_lshl_b32 s7, s7, 7
	s_add_i32 m0, s7, s49
	s_add_i32 s7, s6, 0
	v_add_u32_e32 v0, s7, v14
	v_lshlrev_b32_e32 v0, s28, v0
	v_add_u32_e32 v0, s29, v0
	v_max_i32_e32 v0, 0, v0
	v_lshl_or_b32 v2, v0, 7, v15
	v_lshl_add_u64 v[38:39], s[50:51], 0, v[2:3]
	global_load_lds_dwordx4 v[38:39], off nt
	s_add_i32 s7, s5, 64
	s_and_b32 s7, s7, 511
	s_lshl_b32 s7, s7, 7
	s_add_i32 m0, s7, s49
	s_add_i32 s7, s6, 64
	v_add_u32_e32 v0, s7, v14
	v_lshlrev_b32_e32 v0, s28, v0
	v_add_u32_e32 v0, s29, v0
	v_max_i32_e32 v0, 0, v0
	v_lshl_or_b32 v2, v0, 7, v15
	v_lshl_add_u64 v[40:41], s[50:51], 0, v[2:3]
	global_load_lds_dwordx4 v[40:41], off nt
.Latt_half_9:
	s_add_i32 s7, s5, 128
	s_and_b32 s7, s7, 511
	s_lshl_b32 s7, s7, 7
	s_add_i32 m0, s7, s49
	s_add_i32 s7, s6, 128
	v_add_u32_e32 v0, s7, v14
	v_lshlrev_b32_e32 v0, s28, v0
	v_add_u32_e32 v0, s29, v0
	v_max_i32_e32 v0, 0, v0
	v_lshl_or_b32 v2, v0, 7, v15
	v_lshl_add_u64 v[42:43], s[50:51], 0, v[2:3]
	global_load_lds_dwordx4 v[42:43], off nt
	s_add_i32 s7, s5, 192
	s_and_b32 s7, s7, 511
	s_lshl_b32 s7, s7, 7
	s_add_i32 m0, s7, s49
	s_add_i32 s7, s6, 192
	v_add_u32_e32 v0, s7, v14
	v_lshlrev_b32_e32 v0, s28, v0
	v_add_u32_e32 v0, s29, v0
	v_max_i32_e32 v0, 0, v0
	v_lshl_or_b32 v2, v0, 7, v15
	v_lshl_add_u64 v[44:45], s[50:51], 0, v[2:3]
	global_load_lds_dwordx4 v[44:45], off nt
	s_waitcnt vmcnt(0)
	s_barrier

.Latt_blk:
	s_lshr_b32 s11, s53, 4
	s_and_b32 s12, s53, 15
	s_lshl_b32 s20, s11, 1
	s_lshl_b32 s13, s64, 4
	s_add_i32 s13, s13, s12
	s_lshr_b32 s14, s12, 2
	s_and_b32 s15, s12, 3
	s_lshl_b32 s16, s64, 2
	s_add_i32 s15, s16, s15
	s_cmp_eq_u32 s11, 1
	s_cselect_b32 s21, s14, 0
	s_cselect_b32 s24, s15, s13
	s_cmp_eq_u32 s11, 2
	s_cselect_b32 s21, s12, s21
	s_cselect_b32 s24, s64, s24
	s_add_i32 s4, s53, 1
	s_min_u32 s4, s4, 47
	s_lshr_b32 s11, s4, 4
	s_and_b32 s12, s4, 15
	s_lshl_b32 s28, s11, 1
	s_lshl_b32 s13, s64, 4
	s_add_i32 s13, s13, s12
	s_lshr_b32 s14, s12, 2
	s_and_b32 s15, s12, 3
	s_lshl_b32 s16, s64, 2
	s_add_i32 s15, s16, s15
	s_cmp_eq_u32 s11, 1
	s_cselect_b32 s29, s14, 0
	s_cselect_b32 s30, s15, s13
	s_cmp_eq_u32 s11, 2
	s_cselect_b32 s29, s12, s29
	s_cselect_b32 s30, s64, s30
	s_lshr_b32 s11, s4, 4
	s_and_b32 s12, s4, 15
	s_and_b32 s13, s12, 3
	s_cmp_lg_u32 s12, 0
	s_cselect_b32 s14, 1, 0
	s_lshr_b32 s15, s12, 2
	s_and_b32 s16, s12, 3
	s_add_i32 s15, s15, s16
	s_add_i32 s15, s15, 1
	s_and_b32 s15, s15, 3
	s_cmp_lg_u32 s16, 0
	s_cselect_b32 s16, 1, 0
	s_cmp_eq_u32 s11, 1
	s_cselect_b32 s13, s15, s13
	s_cselect_b32 s14, s16, s14
	s_and_b32 s15, s12, 1
	s_lshl_b32 s15, s15, 1
	s_add_i32 s15, s15, 1
	s_cmp_eq_u32 s11, 2
	s_cselect_b32 s88, s15, s13
	s_cselect_b32 s89, 0, s14
	s_lshl_b32 s5, s88, 7
	s_lshl_b32 s6, s67, 3
	s_add_i32 s5, s5, s6
	s_add_i32 s6, s30, -1
	s_lshl_b32 s6, s6, 7
	s_cmp_eq_u32 s89, 1
	s_cbranch_scc1 .Latt_half_10
	s_add_i32 s7, s5, 0
	s_and_b32 s7, s7, 511
	s_lshl_b32 s7, s7, 7
	s_add_i32 m0, s7, s48
	s_add_i32 s7, s6, 0
	v_add_u32_e32 v0, s7, v14
	v_lshlrev_b32_e32 v0, s28, v0
	v_add_u32_e32 v0, s29, v0
	v_max_i32_e32 v0, 0, v0
	v_lshl_or_b32 v2, v0, 7, v15
	v_lshl_add_u64 v[38:39], s[46:47], 0, v[2:3]
	global_load_lds_dwordx4 v[38:39], off nt
	s_add_i32 s7, s5, 64
	s_and_b32 s7, s7, 511
	s_lshl_b32 s7, s7, 7
	s_add_i32 m0, s7, s48
	s_add_i32 s7, s6, 64
	v_add_u32_e32 v0, s7, v14
	v_lshlrev_b32_e32 v0, s28, v0
	v_add_u32_e32 v0, s29, v0
	v_max_i32_e32 v0, 0, v0
	v_lshl_or_b32 v2, v0, 7, v15
	v_lshl_add_u64 v[40:41], s[46:47], 0, v[2:3]
	global_load_lds_dwordx4 v[40:41], off nt
.Latt_half_10:
	s_add_i32 s7, s5, 128
	s_and_b32 s7, s7, 511
	s_lshl_b32 s7, s7, 7
	s_add_i32 m0, s7, s48
	s_add_i32 s7, s6, 128
	v_add_u32_e32 v0, s7, v14
	v_lshlrev_b32_e32 v0, s28, v0
	v_add_u32_e32 v0, s29, v0
	v_max_i32_e32 v0, 0, v0
	v_lshl_or_b32 v2, v0, 7, v15
	v_lshl_add_u64 v[42:43], s[46:47], 0, v[2:3]
	global_load_lds_dwordx4 v[42:43], off nt
	s_add_i32 s7, s5, 192
	s_and_b32 s7, s7, 511
	s_lshl_b32 s7, s7, 7
	s_add_i32 m0, s7, s48
	s_add_i32 s7, s6, 192
	v_add_u32_e32 v0, s7, v14
	v_lshlrev_b32_e32 v0, s28, v0
	v_add_u32_e32 v0, s29, v0
	v_max_i32_e32 v0, 0, v0
	v_lshl_or_b32 v2, v0, 7, v15
	v_lshl_add_u64 v[44:45], s[46:47], 0, v[2:3]
	global_load_lds_dwordx4 v[44:45], off nt
	s_lshr_b32 s11, s53, 4
	s_and_b32 s12, s53, 15
	s_and_b32 s13, s12, 3
	s_cmp_lg_u32 s12, 0
	s_cselect_b32 s14, 1, 0
	s_lshr_b32 s15, s12, 2
	s_and_b32 s16, s12, 3
	s_add_i32 s15, s15, s16
	s_add_i32 s15, s15, 1
	s_and_b32 s15, s15, 3
	s_cmp_lg_u32 s16, 0
	s_cselect_b32 s16, 1, 0
	s_cmp_eq_u32 s11, 1
	s_cselect_b32 s13, s15, s13
	s_cselect_b32 s14, s16, s14
	s_and_b32 s15, s12, 1
	s_lshl_b32 s15, s15, 1
	s_add_i32 s15, s15, 1
	s_cmp_eq_u32 s11, 2
	s_cselect_b32 s90, s15, s13
	s_cselect_b32 s31, 0, s14
	s_lshl_b32 s91, s90, 3
	s_add_i32 s91, s91, s67
	s_add_i32 s5, s91, 0
	s_and_b32 s5, s5, 31
	s_lshl_b32 s5, s5, 11
	v_add_u32_e32 v0, s5, v4
	v_add_u32_e32 v1, s5, v5
	ds_read_b128 v[84:87], v0
	ds_read_b128 v[88:91], v1
	s_add_i32 s5, s91, 1
	s_and_b32 s5, s5, 31
	s_lshl_b32 s5, s5, 11
	v_add_u32_e32 v0, s5, v4
	v_add_u32_e32 v1, s5, v5
	ds_read_b128 v[92:95], v0
	ds_read_b128 v[96:99], v1
	s_add_i32 s5, s91, 2
	s_and_b32 s5, s5, 31
	s_lshl_b32 s5, s5, 11
	v_add_u32_e32 v0, s5, v4
	v_add_u32_e32 v1, s5, v5
	ds_read_b128 v[100:103], v0
	ds_read_b128 v[104:107], v1
	s_add_i32 s5, s91, 3
	s_and_b32 s5, s5, 31
	s_lshl_b32 s5, s5, 11
	v_add_u32_e32 v0, s5, v4
	v_add_u32_e32 v1, s5, v5
	ds_read_b128 v[108:111], v0
	ds_read_b128 v[112:115], v1
	s_add_i32 s5, s91, 4
	s_and_b32 s5, s5, 31
	s_lshl_b32 s5, s5, 11
	v_add_u32_e32 v0, s5, v4
	v_add_u32_e32 v1, s5, v5
	ds_read_b128 v[116:119], v0
	ds_read_b128 v[120:123], v1
	s_add_i32 s5, s91, 5
	s_and_b32 s5, s5, 31
	s_lshl_b32 s5, s5, 11
	v_add_u32_e32 v0, s5, v4
	v_add_u32_e32 v1, s5, v5
	ds_read_b128 v[124:127], v0
	ds_read_b128 v[128:131], v1
	s_lshl_b32 s5, 1, s20
	v_cvt_f32_u32_e32 v0, s5
	v_mul_f32_e32 v21, v20, v0
	v_xor_b32_e32 v0, 0x80000000, v21
	v_mul_f32_e32 v22, v16, v0
	v_add_f32_e32 v23, v21, v22
	v_add_f32_e32 v1, v21, v21
	v_add_f32_e32 v24, v1, v22
	v_fma_f32 v25, v21, v192, v22
	v_mul_f32_e32 v26, 0, v21
	v_mul_f32_e32 v27, 0x41800000, v21
	v_mul_f32_e32 v28, 0x42000000, v21
	v_mul_f32_e32 v29, 0x42400000, v21
	v_mul_f32_e32 v30, 0x42800000, v21
	v_mul_f32_e32 v31, 0x42a00000, v21
	v_mul_f32_e32 v32, 0x42c00000, v21
	v_mul_f32_e32 v33, 0x42e00000, v21
	v_mul_f32_e32 v34, 0x43000000, v21
	s_cmp_eq_u32 s24, 0
	s_cbranch_scc0 .Latt_n0skip_11
	s_cmp_lt_u32 s67, 1
	s_cbranch_scc0 .Latt_n0t_12
	v_mov_b32_e32 v33, v223

.Latt_wj_21:
	s_waitcnt lgkmcnt(0)
	s_barrier
	s_add_i32 s4, s53, 1
	s_add_i32 s4, s4, s52
	s_min_u32 s4, s4, 47
	s_lshr_b32 s11, s4, 4
	s_and_b32 s12, s4, 15
	s_lshl_b32 s28, s11, 1
	s_lshl_b32 s13, s64, 4
	s_add_i32 s13, s13, s12
	s_lshr_b32 s14, s12, 2
	s_and_b32 s15, s12, 3
	s_lshl_b32 s16, s64, 2
	s_add_i32 s15, s16, s15
	s_cmp_eq_u32 s11, 1
	s_cselect_b32 s29, s14, 0
	s_cselect_b32 s30, s15, s13
	s_cmp_eq_u32 s11, 2
	s_cselect_b32 s29, s12, s29
	s_cselect_b32 s30, s64, s30
	s_lshr_b32 s11, s4, 4
	s_and_b32 s12, s4, 15
	s_and_b32 s13, s12, 3
	s_cmp_lg_u32 s12, 0
	s_cselect_b32 s14, 1, 0
	s_lshr_b32 s15, s12, 2
	s_and_b32 s16, s12, 3
	s_add_i32 s15, s15, s16
	s_add_i32 s15, s15, 1
	s_and_b32 s15, s15, 3
	s_cmp_lg_u32 s16, 0
	s_cselect_b32 s16, 1, 0
	s_cmp_eq_u32 s11, 1
	s_cselect_b32 s13, s15, s13
	s_cselect_b32 s14, s16, s14
	s_and_b32 s15, s12, 1
	s_lshl_b32 s15, s15, 1
	s_add_i32 s15, s15, 1
	s_cmp_eq_u32 s11, 2
	s_cselect_b32 s88, s15, s13
	s_cselect_b32 s89, 0, s14
	s_lshl_b32 s5, s88, 7
	s_lshl_b32 s6, s67, 3
	s_add_i32 s5, s5, s6
	s_add_i32 s6, s30, -1
	s_lshl_b32 s6, s6, 7
	s_cmp_eq_u32 s89, 1
	s_cbranch_scc1 .Latt_half_22
	s_add_i32 s7, s5, 0
	s_and_b32 s7, s7, 511
	s_lshl_b32 s7, s7, 7
	s_add_i32 m0, s7, s49
	s_add_i32 s7, s6, 0
	v_add_u32_e32 v0, s7, v14
	v_lshlrev_b32_e32 v0, s28, v0
	v_add_u32_e32 v0, s29, v0
	v_max_i32_e32 v0, 0, v0
	v_lshl_or_b32 v2, v0, 7, v15
	v_lshl_add_u64 v[38:39], s[50:51], 0, v[2:3]
	global_load_lds_dwordx4 v[38:39], off nt
	s_add_i32 s7, s5, 64
	s_and_b32 s7, s7, 511
	s_lshl_b32 s7, s7, 7
	s_add_i32 m0, s7, s49
	s_add_i32 s7, s6, 64
	v_add_u32_e32 v0, s7, v14
	v_lshlrev_b32_e32 v0, s28, v0
	v_add_u32_e32 v0, s29, v0
	v_max_i32_e32 v0, 0, v0
	v_lshl_or_b32 v2, v0, 7, v15
	v_lshl_add_u64 v[40:41], s[50:51], 0, v[2:3]
	global_load_lds_dwordx4 v[40:41], off nt
.Latt_half_22:
	s_add_i32 s7, s5, 128
	s_and_b32 s7, s7, 511
	s_lshl_b32 s7, s7, 7
	s_add_i32 m0, s7, s49
	s_add_i32 s7, s6, 128
	v_add_u32_e32 v0, s7, v14
	v_lshlrev_b32_e32 v0, s28, v0
	v_add_u32_e32 v0, s29, v0
	v_max_i32_e32 v0, 0, v0
	v_lshl_or_b32 v2, v0, 7, v15
	v_lshl_add_u64 v[42:43], s[50:51], 0, v[2:3]
	global_load_lds_dwordx4 v[42:43], off nt
	s_add_i32 s7, s5, 192
	s_and_b32 s7, s7, 511
	s_lshl_b32 s7, s7, 7
	s_add_i32 m0, s7, s49
	s_add_i32 s7, s6, 192
	v_add_u32_e32 v0, s7, v14
	v_lshlrev_b32_e32 v0, s28, v0
	v_add_u32_e32 v0, s29, v0
	v_max_i32_e32 v0, 0, v0
	v_lshl_or_b32 v2, v0, 7, v15
	v_lshl_add_u64 v[44:45], s[50:51], 0, v[2:3]
	global_load_lds_dwordx4 v[44:45], off nt
	s_add_i32 s4, s53, 2
	s_min_u32 s4, s4, 47
	s_lshr_b32 s11, s4, 4
	s_and_b32 s12, s4, 15
	s_lshl_b32 s8, s11, 1
	s_lshl_b32 s13, s64, 4
	s_add_i32 s13, s13, s12
	s_lshr_b32 s14, s12, 2
	s_and_b32 s15, s12, 3
	s_lshl_b32 s16, s64, 2
	s_add_i32 s15, s16, s15
	s_cmp_eq_u32 s11, 1
	s_cselect_b32 s17, s14, 0
	s_cselect_b32 s10, s15, s13
	s_cmp_eq_u32 s11, 2
	s_cselect_b32 s17, s12, s17
	s_cselect_b32 s10, s64, s10
	s_lshl_b32 s5, s10, 7
	v_add_u32_e32 v82, s5, v17
	v_lshlrev_b32_e32 v82, s8, v82
	v_add_u32_e32 v82, s17, v82
	v_lshl_add_u32 v1, v82, 11, v18
	global_load_dwordx4 v[48:51], v1, s[40:41]
	global_load_dwordx4 v[52:55], v1, s[40:41] offset:64
	s_add_i32 s5, s91, 0
	s_and_b32 s5, s5, 31
	s_lshl_b32 s5, s5, 11
	v_add_u32_e32 v37, s5, v6
	v_add_u32_e32 v38, s5, v7
	v_add_u32_e32 v39, s5, v8
	v_add_u32_e32 v40, s5, v9
	ds_read_b64_tr_b16 v[84:85], v37
	ds_read_b64_tr_b16 v[88:89], v38
	ds_read_b64_tr_b16 v[92:93], v39
	ds_read_b64_tr_b16 v[96:97], v40
	s_add_i32 s5, s91, 1
	s_and_b32 s5, s5, 31
	s_lshl_b32 s5, s5, 11
	v_add_u32_e32 v37, s5, v6
	v_add_u32_e32 v38, s5, v7
	v_add_u32_e32 v39, s5, v8
	v_add_u32_e32 v40, s5, v9
	ds_read_b64_tr_b16 v[86:87], v37
	ds_read_b64_tr_b16 v[90:91], v38
	ds_read_b64_tr_b16 v[94:95], v39
	ds_read_b64_tr_b16 v[98:99], v40
	s_add_i32 s5, s91, 2
	s_and_b32 s5, s5, 31
	s_lshl_b32 s5, s5, 11
	v_add_u32_e32 v37, s5, v6
	v_add_u32_e32 v38, s5, v7
	v_add_u32_e32 v39, s5, v8
	v_add_u32_e32 v40, s5, v9
	ds_read_b64_tr_b16 v[100:101], v37
	ds_read_b64_tr_b16 v[104:105], v38
	ds_read_b64_tr_b16 v[108:109], v39
	ds_read_b64_tr_b16 v[112:113], v40
	s_add_i32 s5, s91, 3
	s_and_b32 s5, s5, 31
	s_lshl_b32 s5, s5, 11
	v_add_u32_e32 v37, s5, v6
	v_add_u32_e32 v38, s5, v7
	v_add_u32_e32 v39, s5, v8
	v_add_u32_e32 v40, s5, v9
	ds_read_b64_tr_b16 v[102:103], v37
	ds_read_b64_tr_b16 v[106:107], v38
	ds_read_b64_tr_b16 v[110:111], v39
	ds_read_b64_tr_b16 v[114:115], v40
	s_waitcnt lgkmcnt(8)
	v_mfma_f32_16x16x32_bf16 v[228:231], v[84:87], v[172:175], 0
	v_mfma_f32_16x16x32_bf16 v[232:235], v[88:91], v[172:175], 0
	v_mfma_f32_16x16x32_bf16 v[236:239], v[92:95], v[172:175], 0
	v_mfma_f32_16x16x32_bf16 v[240:243], v[96:99], v[172:175], 0
	s_add_i32 s5, s91, 4
	s_and_b32 s5, s5, 31
	s_lshl_b32 s5, s5, 11
	v_add_u32_e32 v37, s5, v6
	v_add_u32_e32 v38, s5, v7
	v_add_u32_e32 v39, s5, v8
	v_add_u32_e32 v40, s5, v9
	ds_read_b64_tr_b16 v[84:85], v37
	ds_read_b64_tr_b16 v[88:89], v38
	ds_read_b64_tr_b16 v[92:93], v39
	ds_read_b64_tr_b16 v[96:97], v40
	s_add_i32 s5, s91, 5
	s_and_b32 s5, s5, 31
	s_lshl_b32 s5, s5, 11
	v_add_u32_e32 v37, s5, v6
	v_add_u32_e32 v38, s5, v7
	v_add_u32_e32 v39, s5, v8
	v_add_u32_e32 v40, s5, v9
	ds_read_b64_tr_b16 v[86:87], v37
	ds_read_b64_tr_b16 v[90:91], v38
	ds_read_b64_tr_b16 v[94:95], v39
	ds_read_b64_tr_b16 v[98:99], v40
	s_waitcnt lgkmcnt(8)
	v_mfma_f32_16x16x32_bf16 v[228:231], v[100:103], v[176:179], v[228:231]
	v_mfma_f32_16x16x32_bf16 v[232:235], v[104:107], v[176:179], v[232:235]
	v_mfma_f32_16x16x32_bf16 v[236:239], v[108:111], v[176:179], v[236:239]
	v_mfma_f32_16x16x32_bf16 v[240:243], v[112:115], v[176:179], v[240:243]
	s_add_i32 s5, s91, 6
	s_and_b32 s5, s5, 31
	s_lshl_b32 s5, s5, 11
	v_add_u32_e32 v37, s5, v6
	v_add_u32_e32 v38, s5, v7
	v_add_u32_e32 v39, s5, v8
	v_add_u32_e32 v40, s5, v9
	ds_read_b64_tr_b16 v[100:101], v37
	ds_read_b64_tr_b16 v[104:105], v38
	ds_read_b64_tr_b16 v[108:109], v39
	ds_read_b64_tr_b16 v[112:113], v40
	s_add_i32 s5, s91, 7
	s_and_b32 s5, s5, 31
	s_lshl_b32 s5, s5, 11
	v_add_u32_e32 v37, s5, v6
	v_add_u32_e32 v38, s5, v7
	v_add_u32_e32 v39, s5, v8
	v_add_u32_e32 v40, s5, v9
	ds_read_b64_tr_b16 v[102:103], v37
	ds_read_b64_tr_b16 v[106:107], v38
	ds_read_b64_tr_b16 v[110:111], v39
	ds_read_b64_tr_b16 v[114:115], v40
	s_waitcnt lgkmcnt(8)
	v_mfma_f32_16x16x32_bf16 v[228:231], v[84:87], v[180:183], v[228:231]
	v_mfma_f32_16x16x32_bf16 v[232:235], v[88:91], v[180:183], v[232:235]
	v_mfma_f32_16x16x32_bf16 v[236:239], v[92:95], v[180:183], v[236:239]
	v_mfma_f32_16x16x32_bf16 v[240:243], v[96:99], v[180:183], v[240:243]
	s_add_i32 s5, s91, 8
	s_and_b32 s5, s5, 31
	s_lshl_b32 s5, s5, 11
	v_add_u32_e32 v37, s5, v6
	v_add_u32_e32 v38, s5, v7
	v_add_u32_e32 v39, s5, v8
	v_add_u32_e32 v40, s5, v9
	ds_read_b64_tr_b16 v[84:85], v37
	ds_read_b64_tr_b16 v[88:89], v38
	ds_read_b64_tr_b16 v[92:93], v39
	ds_read_b64_tr_b16 v[96:97], v40
	s_add_i32 s5, s67, 9
	s_min_u32 s5, s5, 15
	s_lshl_b32 s6, s90, 3
	s_add_i32 s5, s5, s6
	s_and_b32 s5, s5, 31
	s_lshl_b32 s5, s5, 11
	v_add_u32_e32 v37, s5, v6
	v_add_u32_e32 v38, s5, v7
	v_add_u32_e32 v39, s5, v8
	v_add_u32_e32 v40, s5, v9
	ds_read_b64_tr_b16 v[86:87], v37
	ds_read_b64_tr_b16 v[90:91], v38
	ds_read_b64_tr_b16 v[94:95], v39
	ds_read_b64_tr_b16 v[98:99], v40
	s_waitcnt lgkmcnt(8)
	v_mfma_f32_16x16x32_bf16 v[228:231], v[100:103], v[184:187], v[228:231]
	v_mfma_f32_16x16x32_bf16 v[232:235], v[104:107], v[184:187], v[232:235]
	v_mfma_f32_16x16x32_bf16 v[236:239], v[108:111], v[184:187], v[236:239]
	v_mfma_f32_16x16x32_bf16 v[240:243], v[112:115], v[184:187], v[240:243]
	s_waitcnt lgkmcnt(0)
	v_mfma_f32_16x16x32_bf16 v[228:231], v[84:87], v[188:191], v[228:231]
	v_mfma_f32_16x16x32_bf16 v[232:235], v[88:91], v[188:191], v[232:235]
	v_mfma_f32_16x16x32_bf16 v[236:239], v[92:95], v[188:191], v[236:239]
	v_mfma_f32_16x16x32_bf16 v[240:243], v[96:99], v[188:191], v[240:243]
	v_mov_b32_e32 v0, v36
	v_mov_b32_e32 v1, v36
	s_nop 1
	v_permlane16_swap_b32_e32 v0, v1
	s_nop 1
	v_add_f32_e32 v36, v0, v1
	v_mov_b32_e32 v0, v36
	v_mov_b32_e32 v1, v36
	s_nop 1
	v_permlane32_swap_b32_e32 v0, v1
	s_nop 1
	v_add_f32_e32 v36, v0, v1
	s_cmp_lt_u32 s53, 16
	s_cbranch_scc0 .Latt_hasprev_23
	v_mov_b32_e32 v80, v223
	v_mov_b32_e32 v64, 0
	v_mov_b32_e32 v65, 0
	v_mov_b32_e32 v66, 0
	v_mov_b32_e32 v67, 0
	v_mov_b32_e32 v68, 0
	v_mov_b32_e32 v69, 0
	v_mov_b32_e32 v70, 0
	v_mov_b32_e32 v71, 0

.Latt_wj_27:
	s_waitcnt lgkmcnt(0)
	s_barrier
	s_add_i32 s9, s53, 1
	s_lshr_b32 s11, s9, 4
	s_and_b32 s12, s9, 15
	s_lshl_b32 s20, s11, 1
	s_lshl_b32 s13, s64, 4
	s_add_i32 s13, s13, s12
	s_lshr_b32 s14, s12, 2
	s_and_b32 s15, s12, 3
	s_lshl_b32 s16, s64, 2
	s_add_i32 s15, s16, s15
	s_cmp_eq_u32 s11, 1
	s_cselect_b32 s21, s14, 0
	s_cselect_b32 s24, s15, s13
	s_cmp_eq_u32 s11, 2
	s_cselect_b32 s21, s12, s21
	s_cselect_b32 s24, s64, s24
	s_add_i32 s4, s9, 1
	s_min_u32 s4, s4, 47
	s_lshr_b32 s11, s4, 4
	s_and_b32 s12, s4, 15
	s_lshl_b32 s28, s11, 1
	s_lshl_b32 s13, s64, 4
	s_add_i32 s13, s13, s12
	s_lshr_b32 s14, s12, 2
	s_and_b32 s15, s12, 3
	s_lshl_b32 s16, s64, 2
	s_add_i32 s15, s16, s15
	s_cmp_eq_u32 s11, 1
	s_cselect_b32 s29, s14, 0
	s_cselect_b32 s30, s15, s13
	s_cmp_eq_u32 s11, 2
	s_cselect_b32 s29, s12, s29
	s_cselect_b32 s30, s64, s30
	s_lshr_b32 s11, s4, 4
	s_and_b32 s12, s4, 15
	s_and_b32 s13, s12, 3
	s_cmp_lg_u32 s12, 0
	s_cselect_b32 s14, 1, 0
	s_lshr_b32 s15, s12, 2
	s_and_b32 s16, s12, 3
	s_add_i32 s15, s15, s16
	s_add_i32 s15, s15, 1
	s_and_b32 s15, s15, 3
	s_cmp_lg_u32 s16, 0
	s_cselect_b32 s16, 1, 0
	s_cmp_eq_u32 s11, 1
	s_cselect_b32 s13, s15, s13
	s_cselect_b32 s14, s16, s14
	s_and_b32 s15, s12, 1
	s_lshl_b32 s15, s15, 1
	s_add_i32 s15, s15, 1
	s_cmp_eq_u32 s11, 2
	s_cselect_b32 s88, s15, s13
	s_cselect_b32 s89, 0, s14
	s_lshl_b32 s5, s88, 7
	s_lshl_b32 s6, s67, 3
	s_add_i32 s5, s5, s6
	s_add_i32 s6, s30, -1
	s_lshl_b32 s6, s6, 7
	s_cmp_eq_u32 s89, 1
	s_cbranch_scc1 .Latt_half_28
	s_add_i32 s7, s5, 0
	s_and_b32 s7, s7, 511
	s_lshl_b32 s7, s7, 7
	s_add_i32 m0, s7, s48
	s_add_i32 s7, s6, 0
	v_add_u32_e32 v0, s7, v14
	v_lshlrev_b32_e32 v0, s28, v0
	v_add_u32_e32 v0, s29, v0
	v_max_i32_e32 v0, 0, v0
	v_lshl_or_b32 v2, v0, 7, v15
	v_lshl_add_u64 v[38:39], s[46:47], 0, v[2:3]
	global_load_lds_dwordx4 v[38:39], off nt
	s_add_i32 s7, s5, 64
	s_and_b32 s7, s7, 511
	s_lshl_b32 s7, s7, 7
	s_add_i32 m0, s7, s48
	s_add_i32 s7, s6, 64
	v_add_u32_e32 v0, s7, v14
	v_lshlrev_b32_e32 v0, s28, v0
	v_add_u32_e32 v0, s29, v0
	v_max_i32_e32 v0, 0, v0
	v_lshl_or_b32 v2, v0, 7, v15
	v_lshl_add_u64 v[40:41], s[46:47], 0, v[2:3]
	global_load_lds_dwordx4 v[40:41], off nt
.Latt_half_28:
	s_add_i32 s7, s5, 128
	s_and_b32 s7, s7, 511
	s_lshl_b32 s7, s7, 7
	s_add_i32 m0, s7, s48
	s_add_i32 s7, s6, 128
	v_add_u32_e32 v0, s7, v14
	v_lshlrev_b32_e32 v0, s28, v0
	v_add_u32_e32 v0, s29, v0
	v_max_i32_e32 v0, 0, v0
	v_lshl_or_b32 v2, v0, 7, v15
	v_lshl_add_u64 v[42:43], s[46:47], 0, v[2:3]
	global_load_lds_dwordx4 v[42:43], off nt
	s_add_i32 s7, s5, 192
	s_and_b32 s7, s7, 511
	s_lshl_b32 s7, s7, 7
	s_add_i32 m0, s7, s48
	s_add_i32 s7, s6, 192
	v_add_u32_e32 v0, s7, v14
	v_lshlrev_b32_e32 v0, s28, v0
	v_add_u32_e32 v0, s29, v0
	v_max_i32_e32 v0, 0, v0
	v_lshl_or_b32 v2, v0, 7, v15
	v_lshl_add_u64 v[44:45], s[46:47], 0, v[2:3]
	global_load_lds_dwordx4 v[44:45], off nt
	s_lshr_b32 s11, s9, 4
	s_and_b32 s12, s9, 15
	s_and_b32 s13, s12, 3
	s_cmp_lg_u32 s12, 0
	s_cselect_b32 s14, 1, 0
	s_lshr_b32 s15, s12, 2
	s_and_b32 s16, s12, 3
	s_add_i32 s15, s15, s16
	s_add_i32 s15, s15, 1
	s_and_b32 s15, s15, 3
	s_cmp_lg_u32 s16, 0
	s_cselect_b32 s16, 1, 0
	s_cmp_eq_u32 s11, 1
	s_cselect_b32 s13, s15, s13
	s_cselect_b32 s14, s16, s14
	s_and_b32 s15, s12, 1
	s_lshl_b32 s15, s15, 1
	s_add_i32 s15, s15, 1
	s_cmp_eq_u32 s11, 2
	s_cselect_b32 s90, s15, s13
	s_cselect_b32 s31, 0, s14
	s_lshl_b32 s91, s90, 3
	s_add_i32 s91, s91, s67
	s_add_i32 s5, s91, 0
	s_and_b32 s5, s5, 31
	s_lshl_b32 s5, s5, 11
	v_add_u32_e32 v0, s5, v4
	v_add_u32_e32 v1, s5, v5
	ds_read_b128 v[84:87], v0
	ds_read_b128 v[88:91], v1
	s_add_i32 s5, s91, 1
	s_and_b32 s5, s5, 31
	s_lshl_b32 s5, s5, 11
	v_add_u32_e32 v0, s5, v4
	v_add_u32_e32 v1, s5, v5
	ds_read_b128 v[92:95], v0
	ds_read_b128 v[96:99], v1
	s_add_i32 s5, s91, 2
	s_and_b32 s5, s5, 31
	s_lshl_b32 s5, s5, 11
	v_add_u32_e32 v0, s5, v4
	v_add_u32_e32 v1, s5, v5
	ds_read_b128 v[100:103], v0
	ds_read_b128 v[104:107], v1
	s_add_i32 s5, s91, 3
	s_and_b32 s5, s5, 31
	s_lshl_b32 s5, s5, 11
	v_add_u32_e32 v0, s5, v4
	v_add_u32_e32 v1, s5, v5
	ds_read_b128 v[108:111], v0
	ds_read_b128 v[112:115], v1
	s_add_i32 s5, s91, 4
	s_and_b32 s5, s5, 31
	s_lshl_b32 s5, s5, 11
	v_add_u32_e32 v0, s5, v4
	v_add_u32_e32 v1, s5, v5
	ds_read_b128 v[116:119], v0
	ds_read_b128 v[120:123], v1
	s_add_i32 s5, s91, 5
	s_and_b32 s5, s5, 31
	s_lshl_b32 s5, s5, 11
	v_add_u32_e32 v0, s5, v4
	v_add_u32_e32 v1, s5, v5
	ds_read_b128 v[124:127], v0
	ds_read_b128 v[128:131], v1
	s_lshl_b32 s5, 1, s20
	v_cvt_f32_u32_e32 v0, s5
	v_mul_f32_e32 v21, v20, v0
	v_xor_b32_e32 v0, 0x80000000, v21
	v_mul_f32_e32 v22, v16, v0
	v_add_f32_e32 v23, v21, v22
	v_add_f32_e32 v1, v21, v21
	v_add_f32_e32 v24, v1, v22
	v_fma_f32 v25, v21, v192, v22
	v_mul_f32_e32 v26, 0, v21
	v_mul_f32_e32 v27, 0x41800000, v21
	v_mul_f32_e32 v28, 0x42000000, v21
	v_mul_f32_e32 v29, 0x42400000, v21
	v_mul_f32_e32 v30, 0x42800000, v21
	v_mul_f32_e32 v31, 0x42a00000, v21
	v_mul_f32_e32 v32, 0x42c00000, v21
	v_mul_f32_e32 v33, 0x42e00000, v21
	v_mul_f32_e32 v34, 0x43000000, v21
	s_cmp_eq_u32 s24, 0
	s_cbranch_scc0 .Latt_n0skip_29
	s_cmp_lt_u32 s67, 1
	s_cbranch_scc0 .Latt_n0t_30
	v_mov_b32_e32 v33, v223

.Latt_wj_39:
	s_waitcnt lgkmcnt(0)
	s_barrier
	s_add_i32 s9, s53, 1
	s_add_i32 s4, s9, 1
	s_add_i32 s4, s4, s52
	s_min_u32 s4, s4, 47
	s_lshr_b32 s11, s4, 4
	s_and_b32 s12, s4, 15
	s_lshl_b32 s28, s11, 1
	s_lshl_b32 s13, s64, 4
	s_add_i32 s13, s13, s12
	s_lshr_b32 s14, s12, 2
	s_and_b32 s15, s12, 3
	s_lshl_b32 s16, s64, 2
	s_add_i32 s15, s16, s15
	s_cmp_eq_u32 s11, 1
	s_cselect_b32 s29, s14, 0
	s_cselect_b32 s30, s15, s13
	s_cmp_eq_u32 s11, 2
	s_cselect_b32 s29, s12, s29
	s_cselect_b32 s30, s64, s30
	s_lshr_b32 s11, s4, 4
	s_and_b32 s12, s4, 15
	s_and_b32 s13, s12, 3
	s_cmp_lg_u32 s12, 0
	s_cselect_b32 s14, 1, 0
	s_lshr_b32 s15, s12, 2
	s_and_b32 s16, s12, 3
	s_add_i32 s15, s15, s16
	s_add_i32 s15, s15, 1
	s_and_b32 s15, s15, 3
	s_cmp_lg_u32 s16, 0
	s_cselect_b32 s16, 1, 0
	s_cmp_eq_u32 s11, 1
	s_cselect_b32 s13, s15, s13
	s_cselect_b32 s14, s16, s14
	s_and_b32 s15, s12, 1
	s_lshl_b32 s15, s15, 1
	s_add_i32 s15, s15, 1
	s_cmp_eq_u32 s11, 2
	s_cselect_b32 s88, s15, s13
	s_cselect_b32 s89, 0, s14
	s_lshl_b32 s5, s88, 7
	s_lshl_b32 s6, s67, 3
	s_add_i32 s5, s5, s6
	s_add_i32 s6, s30, -1
	s_lshl_b32 s6, s6, 7
	s_cmp_eq_u32 s89, 1
	s_cbranch_scc1 .Latt_half_40
	s_add_i32 s7, s5, 0
	s_and_b32 s7, s7, 511
	s_lshl_b32 s7, s7, 7
	s_add_i32 m0, s7, s49
	s_add_i32 s7, s6, 0
	v_add_u32_e32 v0, s7, v14
	v_lshlrev_b32_e32 v0, s28, v0
	v_add_u32_e32 v0, s29, v0
	v_max_i32_e32 v0, 0, v0
	v_lshl_or_b32 v2, v0, 7, v15
	v_lshl_add_u64 v[38:39], s[50:51], 0, v[2:3]
	global_load_lds_dwordx4 v[38:39], off nt
	s_add_i32 s7, s5, 64
	s_and_b32 s7, s7, 511
	s_lshl_b32 s7, s7, 7
	s_add_i32 m0, s7, s49
	s_add_i32 s7, s6, 64
	v_add_u32_e32 v0, s7, v14
	v_lshlrev_b32_e32 v0, s28, v0
	v_add_u32_e32 v0, s29, v0
	v_max_i32_e32 v0, 0, v0
	v_lshl_or_b32 v2, v0, 7, v15
	v_lshl_add_u64 v[40:41], s[50:51], 0, v[2:3]
	global_load_lds_dwordx4 v[40:41], off nt
.Latt_half_40:
	s_add_i32 s7, s5, 128
	s_and_b32 s7, s7, 511
	s_lshl_b32 s7, s7, 7
	s_add_i32 m0, s7, s49
	s_add_i32 s7, s6, 128
	v_add_u32_e32 v0, s7, v14
	v_lshlrev_b32_e32 v0, s28, v0
	v_add_u32_e32 v0, s29, v0
	v_max_i32_e32 v0, 0, v0
	v_lshl_or_b32 v2, v0, 7, v15
	v_lshl_add_u64 v[42:43], s[50:51], 0, v[2:3]
	global_load_lds_dwordx4 v[42:43], off nt
	s_add_i32 s7, s5, 192
	s_and_b32 s7, s7, 511
	s_lshl_b32 s7, s7, 7
	s_add_i32 m0, s7, s49
	s_add_i32 s7, s6, 192
	v_add_u32_e32 v0, s7, v14
	v_lshlrev_b32_e32 v0, s28, v0
	v_add_u32_e32 v0, s29, v0
	v_max_i32_e32 v0, 0, v0
	v_lshl_or_b32 v2, v0, 7, v15
	v_lshl_add_u64 v[44:45], s[50:51], 0, v[2:3]
	global_load_lds_dwordx4 v[44:45], off nt
	s_add_i32 s4, s9, 2
	s_min_u32 s4, s4, 47
	s_lshr_b32 s11, s4, 4
	s_and_b32 s12, s4, 15
	s_lshl_b32 s8, s11, 1
	s_lshl_b32 s13, s64, 4
	s_add_i32 s13, s13, s12
	s_lshr_b32 s14, s12, 2
	s_and_b32 s15, s12, 3
	s_lshl_b32 s16, s64, 2
	s_add_i32 s15, s16, s15
	s_cmp_eq_u32 s11, 1
	s_cselect_b32 s17, s14, 0
	s_cselect_b32 s10, s15, s13
	s_cmp_eq_u32 s11, 2
	s_cselect_b32 s17, s12, s17
	s_cselect_b32 s10, s64, s10
	s_lshl_b32 s5, s10, 7
	v_add_u32_e32 v82, s5, v17
	v_lshlrev_b32_e32 v82, s8, v82
	v_add_u32_e32 v82, s17, v82
	v_lshl_add_u32 v1, v82, 11, v18
	global_load_dwordx4 v[56:59], v1, s[40:41]
	global_load_dwordx4 v[60:63], v1, s[40:41] offset:64
	s_add_i32 s5, s91, 0
	s_and_b32 s5, s5, 31
	s_lshl_b32 s5, s5, 11
	v_add_u32_e32 v37, s5, v6
	v_add_u32_e32 v38, s5, v7
	v_add_u32_e32 v39, s5, v8
	v_add_u32_e32 v40, s5, v9
	ds_read_b64_tr_b16 v[84:85], v37
	ds_read_b64_tr_b16 v[88:89], v38
	ds_read_b64_tr_b16 v[92:93], v39
	ds_read_b64_tr_b16 v[96:97], v40
	s_add_i32 s5, s91, 1
	s_and_b32 s5, s5, 31
	s_lshl_b32 s5, s5, 11
	v_add_u32_e32 v37, s5, v6
	v_add_u32_e32 v38, s5, v7
	v_add_u32_e32 v39, s5, v8
	v_add_u32_e32 v40, s5, v9
	ds_read_b64_tr_b16 v[86:87], v37
	ds_read_b64_tr_b16 v[90:91], v38
	ds_read_b64_tr_b16 v[94:95], v39
	ds_read_b64_tr_b16 v[98:99], v40
	s_add_i32 s5, s91, 2
	s_and_b32 s5, s5, 31
	s_lshl_b32 s5, s5, 11
	v_add_u32_e32 v37, s5, v6
	v_add_u32_e32 v38, s5, v7
	v_add_u32_e32 v39, s5, v8
	v_add_u32_e32 v40, s5, v9
	ds_read_b64_tr_b16 v[100:101], v37
	ds_read_b64_tr_b16 v[104:105], v38
	ds_read_b64_tr_b16 v[108:109], v39
	ds_read_b64_tr_b16 v[112:113], v40
	s_add_i32 s5, s91, 3
	s_and_b32 s5, s5, 31
	s_lshl_b32 s5, s5, 11
	v_add_u32_e32 v37, s5, v6
	v_add_u32_e32 v38, s5, v7
	v_add_u32_e32 v39, s5, v8
	v_add_u32_e32 v40, s5, v9
	ds_read_b64_tr_b16 v[102:103], v37
	ds_read_b64_tr_b16 v[106:107], v38
	ds_read_b64_tr_b16 v[110:111], v39
	ds_read_b64_tr_b16 v[114:115], v40
	s_waitcnt lgkmcnt(8)
	v_mfma_f32_16x16x32_bf16 v[228:231], v[84:87], v[172:175], 0
	v_mfma_f32_16x16x32_bf16 v[232:235], v[88:91], v[172:175], 0
	v_mfma_f32_16x16x32_bf16 v[236:239], v[92:95], v[172:175], 0
	v_mfma_f32_16x16x32_bf16 v[240:243], v[96:99], v[172:175], 0
	s_add_i32 s5, s91, 4
	s_and_b32 s5, s5, 31
	s_lshl_b32 s5, s5, 11
	v_add_u32_e32 v37, s5, v6
	v_add_u32_e32 v38, s5, v7
	v_add_u32_e32 v39, s5, v8
	v_add_u32_e32 v40, s5, v9
	ds_read_b64_tr_b16 v[84:85], v37
	ds_read_b64_tr_b16 v[88:89], v38
	ds_read_b64_tr_b16 v[92:93], v39
	ds_read_b64_tr_b16 v[96:97], v40
	s_add_i32 s5, s91, 5
	s_and_b32 s5, s5, 31
	s_lshl_b32 s5, s5, 11
	v_add_u32_e32 v37, s5, v6
	v_add_u32_e32 v38, s5, v7
	v_add_u32_e32 v39, s5, v8
	v_add_u32_e32 v40, s5, v9
	ds_read_b64_tr_b16 v[86:87], v37
	ds_read_b64_tr_b16 v[90:91], v38
	ds_read_b64_tr_b16 v[94:95], v39
	ds_read_b64_tr_b16 v[98:99], v40
	s_waitcnt lgkmcnt(8)
	v_mfma_f32_16x16x32_bf16 v[228:231], v[100:103], v[176:179], v[228:231]
	v_mfma_f32_16x16x32_bf16 v[232:235], v[104:107], v[176:179], v[232:235]
	v_mfma_f32_16x16x32_bf16 v[236:239], v[108:111], v[176:179], v[236:239]
	v_mfma_f32_16x16x32_bf16 v[240:243], v[112:115], v[176:179], v[240:243]
	s_add_i32 s5, s91, 6
	s_and_b32 s5, s5, 31
	s_lshl_b32 s5, s5, 11
	v_add_u32_e32 v37, s5, v6
	v_add_u32_e32 v38, s5, v7
	v_add_u32_e32 v39, s5, v8
	v_add_u32_e32 v40, s5, v9
	ds_read_b64_tr_b16 v[100:101], v37
	ds_read_b64_tr_b16 v[104:105], v38
	ds_read_b64_tr_b16 v[108:109], v39
	ds_read_b64_tr_b16 v[112:113], v40
	s_add_i32 s5, s91, 7
	s_and_b32 s5, s5, 31
	s_lshl_b32 s5, s5, 11
	v_add_u32_e32 v37, s5, v6
	v_add_u32_e32 v38, s5, v7
	v_add_u32_e32 v39, s5, v8
	v_add_u32_e32 v40, s5, v9
	ds_read_b64_tr_b16 v[102:103], v37
	ds_read_b64_tr_b16 v[106:107], v38
	ds_read_b64_tr_b16 v[110:111], v39
	ds_read_b64_tr_b16 v[114:115], v40
	s_waitcnt lgkmcnt(8)
	v_mfma_f32_16x16x32_bf16 v[228:231], v[84:87], v[180:183], v[228:231]
	v_mfma_f32_16x16x32_bf16 v[232:235], v[88:91], v[180:183], v[232:235]
	v_mfma_f32_16x16x32_bf16 v[236:239], v[92:95], v[180:183], v[236:239]
	v_mfma_f32_16x16x32_bf16 v[240:243], v[96:99], v[180:183], v[240:243]
	s_add_i32 s5, s91, 8
	s_and_b32 s5, s5, 31
	s_lshl_b32 s5, s5, 11
	v_add_u32_e32 v37, s5, v6
	v_add_u32_e32 v38, s5, v7
	v_add_u32_e32 v39, s5, v8
	v_add_u32_e32 v40, s5, v9
	ds_read_b64_tr_b16 v[84:85], v37
	ds_read_b64_tr_b16 v[88:89], v38
	ds_read_b64_tr_b16 v[92:93], v39
	ds_read_b64_tr_b16 v[96:97], v40
	s_add_i32 s5, s67, 9
	s_min_u32 s5, s5, 15
	s_lshl_b32 s6, s90, 3
	s_add_i32 s5, s5, s6
	s_and_b32 s5, s5, 31
	s_lshl_b32 s5, s5, 11
	v_add_u32_e32 v37, s5, v6
	v_add_u32_e32 v38, s5, v7
	v_add_u32_e32 v39, s5, v8
	v_add_u32_e32 v40, s5, v9
	ds_read_b64_tr_b16 v[86:87], v37
	ds_read_b64_tr_b16 v[90:91], v38
	ds_read_b64_tr_b16 v[94:95], v39
	ds_read_b64_tr_b16 v[98:99], v40
	s_waitcnt lgkmcnt(8)
	v_mfma_f32_16x16x32_bf16 v[228:231], v[100:103], v[184:187], v[228:231]
	v_mfma_f32_16x16x32_bf16 v[232:235], v[104:107], v[184:187], v[232:235]
	v_mfma_f32_16x16x32_bf16 v[236:239], v[108:111], v[184:187], v[236:239]
	v_mfma_f32_16x16x32_bf16 v[240:243], v[112:115], v[184:187], v[240:243]
	s_waitcnt lgkmcnt(0)
	v_mfma_f32_16x16x32_bf16 v[228:231], v[84:87], v[188:191], v[228:231]
	v_mfma_f32_16x16x32_bf16 v[232:235], v[88:91], v[188:191], v[232:235]
	v_mfma_f32_16x16x32_bf16 v[236:239], v[92:95], v[188:191], v[236:239]
	v_mfma_f32_16x16x32_bf16 v[240:243], v[96:99], v[188:191], v[240:243]
	v_mov_b32_e32 v0, v36
	v_mov_b32_e32 v1, v36
	s_nop 1
	v_permlane16_swap_b32_e32 v0, v1
	s_nop 1
	v_add_f32_e32 v36, v0, v1
	v_mov_b32_e32 v0, v36
	v_mov_b32_e32 v1, v36
	s_nop 1
	v_permlane32_swap_b32_e32 v0, v1
	s_nop 1
	v_add_f32_e32 v36, v0, v1
	s_cmp_lt_u32 s9, 16
	s_cbranch_scc0 .Latt_hasprev_41
	v_mov_b32_e32 v81, v223
	v_mov_b32_e32 v72, 0
	v_mov_b32_e32 v73, 0
	v_mov_b32_e32 v74, 0
	v_mov_b32_e32 v75, 0
	v_mov_b32_e32 v76, 0
	v_mov_b32_e32 v77, 0
	v_mov_b32_e32 v78, 0
	v_mov_b32_e32 v79, 0
